# attention: static s_setprio 1 for younger wave half removed (both units)
# baseline (speedup 1.0000x reference)
.LBB0_628:
	s_and_b32 s96, s84, 15
	s_ashr_i32 s6, s84, 4
	s_xor_b32 s97, s96, 31
	v_mov_b32_e32 v231, v210
	s_and_b64 s[0:1], s[94:95], exec
	s_cselect_b32 s1, s96, s97
	v_readfirstlane_b32 s9, v231
	s_ashr_i32 s10, s9, 6
	s_and_b32 s68, s6, 7
	s_ashr_i32 s7, s6, 31
	s_mul_i32 s4, s6, 0x300000
	s_mul_hi_i32 s0, s6, 0x300000
	s_add_u32 s8, s37, s4
	s_addc_u32 s11, s38, s0
	s_lshl_b32 s0, s6, 10
	s_lshl_b64 s[4:5], s[6:7], 21
	s_and_b32 s6, s0, 0xffffe000
	s_lshl_b32 s0, s1, 8
	v_readlane_b32 s16, v246, 0
	v_writelane_b32 v245, s6, 17
	s_or_b32 s0, s0, s6
	s_lshl_b32 s6, s10, 5
	v_readlane_b32 s20, v246, 4
	v_readlane_b32 s21, v246, 5
	v_and_b32_e32 v227, 63, v231
	v_and_b32_e32 v228, 31, v231
	s_add_i32 s0, s0, s6
	s_mov_b64 s[6:7], s[20:21]
	s_mov_b32 s20, s8
	s_mul_i32 s8, s10, 0x4100
	v_or_b32_e32 v50, s0, v228
	s_add_i32 s8, s8, 0
	s_mul_i32 s16, s68, 0x180
	v_mul_lo_u16_e32 v0, 43, v227
	v_ashrrev_i32_e32 v51, 31, v50
	v_readlane_b32 s17, v246, 1
	s_add_u32 s16, s33, s16
	v_lshrrev_b16_e32 v4, 10, v0
	v_lshl_add_u64 v[2:3], v[50:51], 2, s[92:93]
	s_addc_u32 s17, s36, 0
	v_mul_lo_u16_e32 v0, 24, v4
	global_load_dword v235, v[2:3], off
	v_sub_u16_e32 v0, v227, v0
	v_or_b32_e32 v2, s0, v4
	v_writelane_b32 v245, s16, 18
	v_lshlrev_b32_sdwa v0, v217, v0 dst_sel:DWORD dst_unused:UNUSED_PAD src0_sel:DWORD src1_sel:BYTE_0
	v_mul_u32_u24_e32 v4, 0x190, v4
	v_mov_b64_e32 v[46:47], s[16:17]
	v_writelane_b32 v245, s17, 19
	v_mad_i64_i32 v[2:3], s[16:17], v2, s40, v[46:47]
	v_lshl_add_u64 v[2:3], v[2:3], 0, v[0:1]
	v_add3_u32 v52, s8, v4, v0
	v_or_b32_e32 v0, 64, v227
	v_mul_lo_u16_e32 v4, 43, v0
	v_lshrrev_b16_e32 v10, 10, v4
	v_mul_lo_u16_e32 v4, 24, v10
	v_sub_u16_e32 v0, v0, v4
	v_or_b32_e32 v4, s0, v10
	v_lshlrev_b32_sdwa v0, v217, v0 dst_sel:DWORD dst_unused:UNUSED_PAD src0_sel:DWORD src1_sel:BYTE_0
	v_mul_u32_u24_e32 v10, 0x190, v10
	v_add3_u32 v53, s8, v10, v0
	v_bitop3_b16 v10, v227, s42, v214 bitop3:0xc8
	v_mul_lo_u16_e32 v10, 0xab, v10
	v_mad_i64_i32 v[4:5], s[16:17], v4, s40, v[46:47]
	v_lshrrev_b16_e32 v12, 12, v10
	v_lshl_add_u64 v[6:7], v[4:5], 0, v[0:1]
	v_or_b32_e32 v0, 0xffffff80, v227
	v_mul_lo_u16_e32 v10, 24, v12
	v_sub_u16_e32 v0, v0, v10
	v_or_b32_e32 v10, s0, v12
	v_lshlrev_b32_sdwa v0, v217, v0 dst_sel:DWORD dst_unused:UNUSED_PAD src0_sel:DWORD src1_sel:BYTE_0
	v_mul_u32_u24_e32 v12, 0x190, v12
	v_add3_u32 v54, s8, v12, v0
	v_bitop3_b16 v12, v231, s35, v215 bitop3:0xc8
	v_mul_lo_u16_e32 v12, 0xab, v12
	v_mad_i64_i32 v[10:11], s[16:17], v10, s40, v[46:47]
	v_lshrrev_b16_e32 v18, 12, v12
	v_lshl_add_u64 v[10:11], v[10:11], 0, v[0:1]
	v_or_b32_e32 v0, 0xffffffc0, v231
	v_mul_lo_u16_e32 v12, 24, v18
	v_sub_u16_e32 v0, v0, v12
	v_or_b32_e32 v12, s0, v18
	v_mad_i64_i32 v[12:13], s[16:17], v12, s40, v[46:47]
	v_lshlrev_b32_sdwa v0, v217, v0 dst_sel:DWORD dst_unused:UNUSED_PAD src0_sel:DWORD src1_sel:BYTE_0
	v_mul_u32_u24_e32 v18, 0x190, v18
	v_lshl_add_u64 v[14:15], v[12:13], 0, v[0:1]
	v_add3_u32 v55, s8, v18, v0
	v_or_b32_e32 v0, 0x100, v227
	v_mul_u32_u24_sdwa v20, v0, s43 dst_sel:DWORD dst_unused:UNUSED_PAD src0_sel:WORD_0 src1_sel:DWORD
	v_mul_lo_u16_sdwa v18, v20, v218 dst_sel:DWORD dst_unused:UNUSED_PAD src0_sel:WORD_1 src1_sel:DWORD
	v_sub_u16_e32 v0, v0, v18
	v_or_b32_sdwa v18, s0, v20 dst_sel:DWORD dst_unused:UNUSED_PAD src0_sel:DWORD src1_sel:WORD_1
	v_mad_i64_i32 v[18:19], s[16:17], v18, s40, v[46:47]
	v_lshlrev_b32_e32 v0, 4, v0
	v_mul_u32_u24_sdwa v20, v20, s41 dst_sel:DWORD dst_unused:UNUSED_PAD src0_sel:WORD_1 src1_sel:DWORD
	v_lshl_add_u64 v[18:19], v[18:19], 0, v[0:1]
	v_add3_u32 v56, s8, v20, v0
	v_or_b32_e32 v0, 0x140, v227
	v_mul_u32_u24_sdwa v26, v0, s43 dst_sel:DWORD dst_unused:UNUSED_PAD src0_sel:WORD_0 src1_sel:DWORD
	v_mul_lo_u16_sdwa v20, v26, v218 dst_sel:DWORD dst_unused:UNUSED_PAD src0_sel:WORD_1 src1_sel:DWORD
	v_sub_u16_e32 v0, v0, v20
	v_or_b32_sdwa v20, s0, v26 dst_sel:DWORD dst_unused:UNUSED_PAD src0_sel:DWORD src1_sel:WORD_1
	v_mad_i64_i32 v[20:21], s[16:17], v20, s40, v[46:47]
	v_lshlrev_b32_e32 v0, 4, v0
	v_mul_u32_u24_sdwa v26, v26, s41 dst_sel:DWORD dst_unused:UNUSED_PAD src0_sel:WORD_1 src1_sel:DWORD
	v_lshl_add_u64 v[22:23], v[20:21], 0, v[0:1]
	v_add3_u32 v57, s8, v26, v0
	v_or_b32_e32 v0, 0x180, v227
	v_mul_u32_u24_sdwa v28, v0, s43 dst_sel:DWORD dst_unused:UNUSED_PAD src0_sel:WORD_0 src1_sel:DWORD
	v_mul_lo_u16_sdwa v26, v28, v218 dst_sel:DWORD dst_unused:UNUSED_PAD src0_sel:WORD_1 src1_sel:DWORD
	v_sub_u16_e32 v0, v0, v26
	v_or_b32_sdwa v26, s0, v28 dst_sel:DWORD dst_unused:UNUSED_PAD src0_sel:DWORD src1_sel:WORD_1
	v_mad_i64_i32 v[26:27], s[16:17], v26, s40, v[46:47]
	v_lshlrev_b32_e32 v0, 4, v0
	v_mul_u32_u24_sdwa v28, v28, s41 dst_sel:DWORD dst_unused:UNUSED_PAD src0_sel:WORD_1 src1_sel:DWORD
	v_lshl_add_u64 v[26:27], v[26:27], 0, v[0:1]
	v_add3_u32 v58, s8, v28, v0
	v_or_b32_e32 v0, 0x1c0, v227
	v_mul_u32_u24_sdwa v34, v0, s43 dst_sel:DWORD dst_unused:UNUSED_PAD src0_sel:WORD_0 src1_sel:DWORD
	v_mul_lo_u16_sdwa v28, v34, v218 dst_sel:DWORD dst_unused:UNUSED_PAD src0_sel:WORD_1 src1_sel:DWORD
	v_sub_u16_e32 v0, v0, v28
	v_or_b32_sdwa v28, s0, v34 dst_sel:DWORD dst_unused:UNUSED_PAD src0_sel:DWORD src1_sel:WORD_1
	v_mad_i64_i32 v[28:29], s[16:17], v28, s40, v[46:47]
	v_lshlrev_b32_e32 v0, 4, v0
	v_mul_u32_u24_sdwa v34, v34, s41 dst_sel:DWORD dst_unused:UNUSED_PAD src0_sel:WORD_1 src1_sel:DWORD
	v_lshl_add_u64 v[30:31], v[28:29], 0, v[0:1]
	v_add3_u32 v59, s8, v34, v0
	v_or_b32_e32 v0, 0x200, v227
	v_mul_u32_u24_sdwa v36, v0, s43 dst_sel:DWORD dst_unused:UNUSED_PAD src0_sel:WORD_0 src1_sel:DWORD
	v_mul_lo_u16_sdwa v34, v36, v218 dst_sel:DWORD dst_unused:UNUSED_PAD src0_sel:WORD_1 src1_sel:DWORD
	v_sub_u16_e32 v0, v0, v34
	v_or_b32_sdwa v34, s0, v36 dst_sel:DWORD dst_unused:UNUSED_PAD src0_sel:DWORD src1_sel:WORD_1
	v_mad_i64_i32 v[34:35], s[16:17], v34, s40, v[46:47]
	v_lshlrev_b32_e32 v0, 4, v0
	v_mul_u32_u24_sdwa v36, v36, s41 dst_sel:DWORD dst_unused:UNUSED_PAD src0_sel:WORD_1 src1_sel:DWORD
	v_lshl_add_u64 v[34:35], v[34:35], 0, v[0:1]
	v_add3_u32 v60, s8, v36, v0
	v_or_b32_e32 v0, 0x240, v227
	v_mul_u32_u24_sdwa v42, v0, s43 dst_sel:DWORD dst_unused:UNUSED_PAD src0_sel:WORD_0 src1_sel:DWORD
	v_mul_lo_u16_sdwa v36, v42, v218 dst_sel:DWORD dst_unused:UNUSED_PAD src0_sel:WORD_1 src1_sel:DWORD
	v_sub_u16_e32 v0, v0, v36
	v_or_b32_sdwa v36, s0, v42 dst_sel:DWORD dst_unused:UNUSED_PAD src0_sel:DWORD src1_sel:WORD_1
	v_mad_i64_i32 v[36:37], s[16:17], v36, s40, v[46:47]
	v_lshlrev_b32_e32 v0, 4, v0
	v_mul_u32_u24_sdwa v42, v42, s41 dst_sel:DWORD dst_unused:UNUSED_PAD src0_sel:WORD_1 src1_sel:DWORD
	v_lshl_add_u64 v[38:39], v[36:37], 0, v[0:1]
	v_add3_u32 v61, s8, v42, v0
	v_or_b32_e32 v0, 0x280, v227
	v_mul_u32_u24_sdwa v48, v0, s43 dst_sel:DWORD dst_unused:UNUSED_PAD src0_sel:WORD_0 src1_sel:DWORD
	v_mul_lo_u16_sdwa v42, v48, v218 dst_sel:DWORD dst_unused:UNUSED_PAD src0_sel:WORD_1 src1_sel:DWORD
	v_sub_u16_e32 v0, v0, v42
	v_or_b32_sdwa v42, s0, v48 dst_sel:DWORD dst_unused:UNUSED_PAD src0_sel:DWORD src1_sel:WORD_1
	v_mad_i64_i32 v[42:43], s[16:17], v42, s40, v[46:47]
	v_lshlrev_b32_e32 v0, 4, v0
	v_mul_u32_u24_sdwa v48, v48, s41 dst_sel:DWORD dst_unused:UNUSED_PAD src0_sel:WORD_1 src1_sel:DWORD
	v_lshl_add_u64 v[42:43], v[42:43], 0, v[0:1]
	v_add3_u32 v62, s8, v48, v0
	v_or_b32_e32 v0, 0x2c0, v227
	v_mul_u32_u24_sdwa v63, v0, s43 dst_sel:DWORD dst_unused:UNUSED_PAD src0_sel:WORD_0 src1_sel:DWORD
	v_mul_lo_u16_sdwa v48, v63, v218 dst_sel:DWORD dst_unused:UNUSED_PAD src0_sel:WORD_1 src1_sel:DWORD
	v_sub_u16_e32 v0, v0, v48
	v_or_b32_sdwa v48, s0, v63 dst_sel:DWORD dst_unused:UNUSED_PAD src0_sel:DWORD src1_sel:WORD_1
	global_load_dwordx4 v[2:5], v[2:3], off nt
	s_nop 0
	global_load_dwordx4 v[6:9], v[6:7], off nt
	s_nop 0
	global_load_dwordx4 v[10:13], v[10:11], off nt
	s_nop 0
	global_load_dwordx4 v[14:17], v[14:15], off nt
	s_nop 0
	global_load_dwordx4 v[18:21], v[18:19], off nt
	s_nop 0
	global_load_dwordx4 v[22:25], v[22:23], off nt
	s_nop 0
	global_load_dwordx4 v[26:29], v[26:27], off nt
	s_nop 0
	global_load_dwordx4 v[30:33], v[30:31], off nt
	s_nop 0
	global_load_dwordx4 v[34:37], v[34:35], off nt
	s_nop 0
	global_load_dwordx4 v[38:41], v[38:39], off nt
	v_mad_i64_i32 v[46:47], s[16:17], v48, s40, v[46:47]
	v_lshlrev_b32_e32 v0, 4, v0
	v_lshl_add_u64 v[46:47], v[46:47], 0, v[0:1]
	global_load_dwordx4 v[42:45], v[42:43], off nt
	v_bfe_u32 v237, v231, 5, 1
	global_load_dwordx4 v[46:49], v[46:47], off nt
	s_waitcnt vmcnt(11)
	ds_write_b128 v52, v[2:5]
	s_waitcnt vmcnt(10)
	ds_write_b128 v53, v[6:9]
	s_waitcnt vmcnt(9)
	ds_write_b128 v54, v[10:13]
	s_waitcnt vmcnt(8)
	ds_write_b128 v55, v[14:17]
	s_waitcnt vmcnt(7)
	ds_write_b128 v56, v[18:21]
	s_waitcnt vmcnt(6)
	ds_write_b128 v57, v[22:25]
	s_waitcnt vmcnt(5)
	ds_write_b128 v58, v[26:29]
	s_waitcnt vmcnt(4)
	ds_write_b128 v59, v[30:33]
	s_waitcnt vmcnt(3)
	ds_write_b128 v60, v[34:37]
	s_waitcnt vmcnt(2)
	ds_write_b128 v61, v[38:41]
	s_waitcnt vmcnt(1)
	ds_write_b128 v62, v[42:45]
	v_mul_u32_u24_sdwa v2, v63, s41 dst_sel:DWORD dst_unused:UNUSED_PAD src0_sel:WORD_1 src1_sel:DWORD
	v_add3_u32 v0, s8, v2, v0
	v_lshlrev_b32_e32 v229, 4, v237
	v_lshlrev_b64 v[2:3], 7, v[50:51]
	v_lshl_add_u64 v[50:51], s[62:63], 0, v[2:3]
	v_readlane_b32 s24, v246, 8
	s_waitcnt vmcnt(0)
	ds_write_b128 v0, v[46:49]
	v_mul_u32_u24_e32 v0, 0x190, v228
	v_add3_u32 v0, s8, v0, v229
	ds_read_b128 v[18:21], v0
	ds_read_b128 v[6:9], v0 offset:32
	ds_read_b128 v[14:17], v0 offset:64
	ds_read_b128 v[30:33], v0 offset:128
	ds_read_b128 v[42:45], v0 offset:192
	ds_read_b128 v[38:41], v0 offset:224
	s_waitcnt lgkmcnt(5)
	v_and_b32_e32 v3, 0xffff0000, v18
	v_lshlrev_b32_e32 v2, 16, v18
	v_mul_f32_e32 v112, v3, v3
	v_lshlrev_b32_e32 v4, 16, v19
	v_fmac_f32_e32 v112, v2, v2
	v_and_b32_e32 v5, 0xffff0000, v19
	v_fmac_f32_e32 v112, v4, v4
	v_lshlrev_b32_e32 v10, 16, v20
	v_fmac_f32_e32 v112, v5, v5
	v_and_b32_e32 v11, 0xffff0000, v20
	v_fmac_f32_e32 v112, v10, v10
	v_lshlrev_b32_e32 v12, 16, v21
	v_fmac_f32_e32 v112, v11, v11
	v_and_b32_e32 v13, 0xffff0000, v21
	v_fmac_f32_e32 v112, v12, v12
	v_fmac_f32_e32 v112, v13, v13
	s_waitcnt lgkmcnt(4)
	v_lshlrev_b32_e32 v2, 16, v6
	v_and_b32_e32 v3, 0xffff0000, v6
	v_fmac_f32_e32 v112, v2, v2
	v_lshlrev_b32_e32 v4, 16, v7
	v_fmac_f32_e32 v112, v3, v3
	v_and_b32_e32 v5, 0xffff0000, v7
	v_fmac_f32_e32 v112, v4, v4
	v_lshlrev_b32_e32 v10, 16, v8
	v_fmac_f32_e32 v112, v5, v5
	v_and_b32_e32 v11, 0xffff0000, v8
	v_fmac_f32_e32 v112, v10, v10
	v_lshlrev_b32_e32 v12, 16, v9
	v_fmac_f32_e32 v112, v11, v11
	v_and_b32_e32 v13, 0xffff0000, v9
	v_fmac_f32_e32 v112, v12, v12
	v_fmac_f32_e32 v112, v13, v13
	ds_read_b128 v[10:13], v0 offset:96
	s_waitcnt lgkmcnt(4)
	v_lshlrev_b32_e32 v2, 16, v14
	v_and_b32_e32 v3, 0xffff0000, v14
	v_fmac_f32_e32 v112, v2, v2
	v_lshlrev_b32_e32 v4, 16, v15
	v_fmac_f32_e32 v112, v3, v3
	v_and_b32_e32 v5, 0xffff0000, v15
	v_fmac_f32_e32 v112, v4, v4
	v_lshlrev_b32_e32 v22, 16, v16
	v_fmac_f32_e32 v112, v5, v5
	v_and_b32_e32 v23, 0xffff0000, v16
	v_fmac_f32_e32 v112, v22, v22
	v_lshlrev_b32_e32 v24, 16, v17
	v_fmac_f32_e32 v112, v23, v23
	v_and_b32_e32 v25, 0xffff0000, v17
	v_fmac_f32_e32 v112, v24, v24
	v_fmac_f32_e32 v112, v25, v25
	s_waitcnt lgkmcnt(0)
	v_lshlrev_b32_e32 v2, 16, v10
	v_and_b32_e32 v3, 0xffff0000, v10
	v_fmac_f32_e32 v112, v2, v2
	v_lshlrev_b32_e32 v4, 16, v11
	v_fmac_f32_e32 v112, v3, v3
	v_and_b32_e32 v5, 0xffff0000, v11
	v_fmac_f32_e32 v112, v4, v4
	v_lshlrev_b32_e32 v22, 16, v12
	v_fmac_f32_e32 v112, v5, v5
	v_and_b32_e32 v23, 0xffff0000, v12
	v_fmac_f32_e32 v112, v22, v22
	v_lshlrev_b32_e32 v24, 16, v13
	v_fmac_f32_e32 v112, v23, v23
	v_and_b32_e32 v25, 0xffff0000, v13
	v_fmac_f32_e32 v112, v24, v24
	v_fmac_f32_e32 v112, v25, v25
	ds_read_b128 v[22:25], v0 offset:160
	v_lshlrev_b32_e32 v2, 16, v30
	v_and_b32_e32 v3, 0xffff0000, v30
	v_fmac_f32_e32 v112, v2, v2
	v_lshlrev_b32_e32 v4, 16, v31
	v_fmac_f32_e32 v112, v3, v3
	v_and_b32_e32 v5, 0xffff0000, v31
	v_fmac_f32_e32 v112, v4, v4
	v_lshlrev_b32_e32 v26, 16, v32
	v_fmac_f32_e32 v112, v5, v5
	v_and_b32_e32 v27, 0xffff0000, v32
	v_fmac_f32_e32 v112, v26, v26
	v_lshlrev_b32_e32 v28, 16, v33
	v_fmac_f32_e32 v112, v27, v27
	v_and_b32_e32 v29, 0xffff0000, v33
	v_fmac_f32_e32 v112, v28, v28
	v_fmac_f32_e32 v112, v29, v29
	s_waitcnt lgkmcnt(0)
	v_lshlrev_b32_e32 v2, 16, v22
	v_and_b32_e32 v3, 0xffff0000, v22
	v_fmac_f32_e32 v112, v2, v2
	v_lshlrev_b32_e32 v4, 16, v23
	v_fmac_f32_e32 v112, v3, v3
	v_and_b32_e32 v5, 0xffff0000, v23
	v_fmac_f32_e32 v112, v4, v4
	v_lshlrev_b32_e32 v26, 16, v24
	v_fmac_f32_e32 v112, v5, v5
	v_and_b32_e32 v27, 0xffff0000, v24
	v_fmac_f32_e32 v112, v26, v26
	v_lshlrev_b32_e32 v28, 16, v25
	v_fmac_f32_e32 v112, v27, v27
	v_and_b32_e32 v29, 0xffff0000, v25
	v_fmac_f32_e32 v112, v28, v28
	v_fmac_f32_e32 v112, v29, v29
	v_lshlrev_b32_e32 v2, 16, v42
	v_and_b32_e32 v3, 0xffff0000, v42
	v_fmac_f32_e32 v112, v2, v2
	v_lshlrev_b32_e32 v4, 16, v43
	v_fmac_f32_e32 v112, v3, v3
	v_and_b32_e32 v5, 0xffff0000, v43
	v_fmac_f32_e32 v112, v4, v4
	v_lshlrev_b32_e32 v26, 16, v44
	v_fmac_f32_e32 v112, v5, v5
	v_and_b32_e32 v27, 0xffff0000, v44
	v_fmac_f32_e32 v112, v26, v26
	v_lshlrev_b32_e32 v28, 16, v45
	v_fmac_f32_e32 v112, v27, v27
	v_and_b32_e32 v29, 0xffff0000, v45
	v_fmac_f32_e32 v112, v28, v28
	v_fmac_f32_e32 v112, v29, v29
	v_lshlrev_b32_e32 v2, 16, v38
	v_and_b32_e32 v3, 0xffff0000, v38
	v_fmac_f32_e32 v112, v2, v2
	v_lshlrev_b32_e32 v4, 16, v39
	v_fmac_f32_e32 v112, v3, v3
	v_and_b32_e32 v5, 0xffff0000, v39
	v_fmac_f32_e32 v112, v4, v4
	v_lshlrev_b32_e32 v34, 16, v40
	v_fmac_f32_e32 v112, v5, v5
	v_and_b32_e32 v35, 0xffff0000, v40
	v_fmac_f32_e32 v112, v34, v34
	ds_read_b128 v[26:29], v0 offset:256
	ds_read_b128 v[2:5], v0 offset:288
	v_fmac_f32_e32 v112, v35, v35
	ds_read_b128 v[46:49], v0 offset:320
	ds_read_b128 v[34:37], v0 offset:352
	v_and_b32_e32 v0, 32, v231
	v_lshl_add_u64 v[52:53], v[50:51], 0, s[44:45]
	v_readlane_b32 s22, v246, 6
	v_readlane_b32 s23, v246, 7
	s_add_u32 s24, s39, s4
	v_lshl_add_u64 v[62:63], s[6:7], 0, v[0:1]
	v_lshl_add_u64 v[54:55], v[50:51], 0, v[0:1]
	v_lshl_add_u64 v[50:51], v[52:53], 0, v[0:1]
	v_or_b32_e32 v0, 64, v0
	s_addc_u32 s4, s34, s5
	v_lshl_add_u64 v[58:59], v[52:53], 0, v[0:1]
	v_lshlrev_b32_e32 v230, 4, v231
	s_and_b32 s21, s11, 0xffff
	s_mov_b32 s22, s14
	s_mov_b32 s23, s15
	v_lshlrev_b32_e32 v113, 16, v41
	v_and_b32_e32 v124, 0xffff0000, v41
	s_waitcnt lgkmcnt(3)
	v_lshlrev_b32_e32 v125, 16, v26
	v_and_b32_e32 v126, 0xffff0000, v26
	v_lshlrev_b32_e32 v128, 16, v27
	v_and_b32_e32 v129, 0xffff0000, v27
	v_lshlrev_b32_e32 v130, 16, v28
	v_and_b32_e32 v131, 0xffff0000, v28
	v_lshlrev_b32_e32 v200, 16, v29
	v_and_b32_e32 v201, 0xffff0000, v29
	s_waitcnt lgkmcnt(2)
	v_lshlrev_b32_e32 v202, 16, v2
	v_and_b32_e32 v203, 0xffff0000, v2
	v_lshlrev_b32_e32 v204, 16, v3
	v_and_b32_e32 v205, 0xffff0000, v3
	v_lshlrev_b32_e32 v206, 16, v4
	v_and_b32_e32 v207, 0xffff0000, v4
	v_lshlrev_b32_e32 v208, 16, v5
	v_and_b32_e32 v209, 0xffff0000, v5
	s_waitcnt lgkmcnt(1)
	v_lshlrev_b32_e32 v232, 16, v46
	v_and_b32_e32 v233, 0xffff0000, v46
	v_lshlrev_b32_e32 v234, 16, v47
	v_and_b32_e32 v236, 0xffff0000, v47
	v_lshlrev_b32_e32 v238, 16, v48
	v_and_b32_e32 v239, 0xffff0000, v48
	v_lshlrev_b32_e32 v240, 16, v49
	v_and_b32_e32 v241, 0xffff0000, v49
	s_waitcnt lgkmcnt(0)
	v_and_b32_e32 v114, 0xffff0000, v34
	v_lshlrev_b32_e32 v115, 16, v34
	v_and_b32_e32 v116, 0xffff0000, v35
	v_lshlrev_b32_e32 v117, 16, v35
	v_and_b32_e32 v118, 0xffff0000, v36
	v_lshlrev_b32_e32 v119, 16, v36
	v_and_b32_e32 v110, 0xffff0000, v37
	v_lshlrev_b32_e32 v111, 16, v37
	flat_load_dwordx4 v[132:135], v[62:63]
	flat_load_dwordx4 v[196:199], v[62:63] offset:16
	flat_load_dwordx4 v[136:139], v[62:63] offset:64
	flat_load_dwordx4 v[192:195], v[62:63] offset:80
	flat_load_dwordx4 v[140:143], v[62:63] offset:128
	flat_load_dwordx4 v[188:191], v[62:63] offset:144
	flat_load_dwordx4 v[144:147], v[62:63] offset:192
	flat_load_dwordx4 v[184:187], v[62:63] offset:208
	flat_load_dwordx4 v[152:155], v[62:63] offset:256
	flat_load_dwordx4 v[180:183], v[62:63] offset:272
	flat_load_dwordx4 v[164:167], v[62:63] offset:320
	flat_load_dwordx4 v[176:179], v[62:63] offset:336
	flat_load_dwordx4 v[172:175], v[62:63] offset:384
	flat_load_dwordx4 v[168:171], v[62:63] offset:400
	flat_load_dwordx4 v[160:163], v[62:63] offset:448
	flat_load_dwordx4 v[156:159], v[62:63] offset:464
	global_load_dwordx4 v[82:85], v[54:55], off offset:16
	global_load_dwordx4 v[98:101], v[54:55], off
	global_load_dwordx4 v[86:89], v[50:51], off offset:16
	global_load_dwordx4 v[102:105], v[50:51], off
	flat_load_dwordx4 v[106:109], v[62:63] offset:512
	flat_load_dwordx4 v[90:93], v[62:63] offset:528
	flat_load_dwordx4 v[148:151], v[62:63] offset:640
	flat_load_dwordx4 v[94:97], v[62:63] offset:656
	s_nop 0
	global_load_dwordx4 v[50:53], v[54:55], off offset:80
	global_load_dwordx4 v[66:69], v[54:55], off offset:64
	s_nop 0
	global_load_dwordx4 v[54:57], v[58:59], off offset:16
	global_load_dwordx4 v[70:73], v[58:59], off
	flat_load_dwordx4 v[74:77], v[62:63] offset:576
	s_nop 0
	flat_load_dwordx4 v[58:61], v[62:63] offset:592
	flat_load_dwordx4 v[78:81], v[62:63] offset:704
	s_nop 0
	flat_load_dwordx4 v[62:65], v[62:63] offset:720
	s_waitcnt lgkmcnt(0)
	s_barrier
	buffer_load_dwordx4 v[120:123], v230, s[20:23], 0 offen
	v_fmac_f32_e32 v112, v113, v113
	v_fmac_f32_e32 v112, v124, v124
	v_fmac_f32_e32 v112, v125, v125
	v_fmac_f32_e32 v112, v126, v126
	buffer_load_dwordx4 v[124:127], v230, s[20:23], s47 offen
	v_fmac_f32_e32 v112, v128, v128
	v_fmac_f32_e32 v112, v129, v129
	v_fmac_f32_e32 v112, v130, v130
	v_fmac_f32_e32 v112, v131, v131
	buffer_load_dwordx4 v[128:131], v230, s[20:23], s48 offen
	v_fmac_f32_e32 v112, v200, v200
	v_fmac_f32_e32 v112, v201, v201
	v_fmac_f32_e32 v112, v202, v202
	v_fmac_f32_e32 v112, v203, v203
	v_fmac_f32_e32 v112, v204, v204
	v_fmac_f32_e32 v112, v205, v205
	v_fmac_f32_e32 v112, v206, v206
	v_fmac_f32_e32 v112, v207, v207
	v_fmac_f32_e32 v112, v208, v208
	v_fmac_f32_e32 v112, v209, v209
	v_fmac_f32_e32 v112, v232, v232
	v_fmac_f32_e32 v112, v233, v233
	v_fmac_f32_e32 v112, v234, v234
	v_fmac_f32_e32 v112, v236, v236
	v_fmac_f32_e32 v112, v238, v238
	v_fmac_f32_e32 v112, v239, v239
	v_fmac_f32_e32 v112, v240, v240
	v_fmac_f32_e32 v112, v241, v241
	v_pk_mul_f32 v[114:115], v[114:115], v[114:115]
	v_mul_hi_i32 v209, v231, s46
	v_add_f32_e32 v0, v115, v112
	v_add_f32_e32 v114, v114, v0
	v_pk_mul_f32 v[112:113], v[116:117], v[116:117]
	v_lshrrev_b32_e32 v233, 31, v209
	v_lshrrev_b32_e32 v209, 2, v209
	v_add_f32_e32 v113, v113, v114
	v_add_u32_e32 v209, v209, v233
	v_readlane_b32 s25, v246, 9
	v_readlane_b32 s26, v246, 10
	v_readlane_b32 s27, v246, 11
	v_and_b32_e32 v0, 0x70, v230
	v_lshlrev_b32_e32 v115, 11, v231
	v_add_f32_e32 v114, v112, v113
	v_pk_mul_f32 v[112:113], v[118:119], v[118:119]
	v_add_lshl_u32 v233, v209, v231, 4
	s_and_b32 s25, s4, 0xffff
	s_mov_b32 s26, s14
	s_mov_b32 s27, s15
	v_and_or_b32 v232, v115, s49, v0
	v_add_f32_e32 v113, v113, v114
	v_add_u32_e32 v209, 0, v233
	buffer_load_dwordx4 v[200:203], v232, s[24:27], 0 offen
	buffer_load_dwordx4 v[204:207], v232, s[24:27], s50 offen
	v_add_f32_e32 v208, v112, v113
	buffer_load_dwordx4 v[112:115], v230, s[20:23], s55 offen
	buffer_load_dwordx4 v[116:119], v230, s[20:23], s56 offen
	v_pk_mul_f32 v[110:111], v[110:111], v[110:111]
	v_readlane_b32 s28, v246, 12
	v_add_f32_e32 v111, v111, v208
	v_add_f32_e32 v110, v110, v111
	ds_bpermute_b32 v111, v212, v110
	s_cmp_gt_i32 s10, 3
	s_mov_b32 s28, s68
	v_readlane_b32 s18, v246, 2
	v_readlane_b32 s19, v246, 3
	s_waitcnt lgkmcnt(0)
	v_add_f32_e32 v110, v110, v111
	v_mul_f32_e32 v111, v235, v235
	v_mul_f32_e32 v110, v111, v110
	v_fmamk_f32 v110, v110, 0x3baaaaab, v216
	v_mul_f32_e32 v111, 0x4b800000, v110
	v_cmp_gt_f32_e32 vcc, s54, v110
	v_readlane_b32 s29, v246, 13
	v_readlane_b32 s30, v246, 14
	v_cndmask_b32_e32 v110, v110, v111, vcc
	v_lshrrev_b32_e32 v111, 3, v231
	v_readlane_b32 s31, v246, 15
	s_waitcnt vmcnt(0)
	ds_write_b128 v209, v[120:123]
	v_add_u32_e32 v209, 0x200, v231
	v_mul_hi_i32 v234, v209, s46
	v_lshrrev_b32_e32 v236, 31, v234
	v_lshrrev_b32_e32 v234, 2, v234
	v_add_u32_e32 v234, v234, v236
	v_add_lshl_u32 v234, v234, v209, 4
	v_add_u32_e32 v236, 0x400, v231
	v_add_u32_e32 v238, 0, v234
	ds_write_b128 v238, v[124:127]
	v_mul_hi_i32 v124, v236, s46
	v_lshrrev_b32_e32 v125, 31, v124
	v_lshrrev_b32_e32 v124, 2, v124
	v_add_u32_e32 v238, v124, v125
	v_add_lshl_u32 v236, v238, v236, 4
	v_add_u32_e32 v238, 0, v236
	buffer_load_dwordx4 v[120:123], v230, s[20:23], s57 offen
	buffer_load_dwordx4 v[124:127], v232, s[24:27], s58 offen
	ds_write_b128 v238, v[128:131]
	buffer_load_dwordx4 v[128:131], v232, s[24:27], s59 offen
	v_lshrrev_b32_e32 v238, 3, v209
	v_mad_u64_u32 v[208:209], s[4:5], v111, s51, v[0:1]
	v_add_u32_e32 v111, 0, v208
	ds_write_b128 v111, v[200:203] offset:25600
	v_mad_u64_u32 v[200:201], s[4:5], v238, s51, v[0:1]
	v_add_u32_e32 v0, 0, v200
	s_cselect_b64 s[4:5], -1, 0
	s_cmp_lt_i32 s10, 4
	ds_write_b128 v0, v[204:207] offset:25600
	s_waitcnt lgkmcnt(0)
	s_barrier
	s_cbranch_scc1 .LBB0_630
	s_nop 0

.LBB0_706:
	s_lshl_b32 s4, s28, 7
	s_and_b64 s[0:1], s[94:95], exec
	v_mov_b32_e32 v208, v210
	s_cselect_b32 s1, s97, s96
	s_lshl_b32 s0, s1, 8
	v_readfirstlane_b32 s6, v208
	s_ashr_i32 s7, s6, 6
	v_readlane_b32 s2, v245, 17
	s_or_b32 s0, s0, s2
	s_lshl_b32 s2, s7, 5
	v_and_b32_e32 v204, 63, v208
	v_and_b32_e32 v205, 31, v208
	s_add_i32 s0, s0, s2
	v_or_b32_e32 v50, s0, v205
	v_mul_lo_u16_e32 v0, 43, v204
	v_ashrrev_i32_e32 v51, 31, v50
	v_lshrrev_b16_e32 v4, 10, v0
	v_readlane_b32 s8, v245, 18
	v_lshl_add_u64 v[2:3], v[50:51], 2, s[92:93]
	v_mul_lo_u16_e32 v0, 24, v4
	v_readlane_b32 s9, v245, 19
	global_load_dword v230, v[2:3], off
	s_mul_i32 s5, s7, 0x4100
	v_sub_u16_e32 v0, v204, v0
	v_or_b32_e32 v2, s0, v4
	v_mov_b64_e32 v[46:47], s[8:9]
	s_add_i32 s5, s5, 0
	v_mad_i64_i32 v[2:3], s[8:9], v2, s40, v[46:47]
	v_lshlrev_b32_sdwa v0, v217, v0 dst_sel:DWORD dst_unused:UNUSED_PAD src0_sel:DWORD src1_sel:BYTE_0
	v_mul_u32_u24_e32 v4, 0x190, v4
	v_lshl_add_u64 v[2:3], v[2:3], 0, v[0:1]
	v_add3_u32 v52, s5, v4, v0
	v_or_b32_e32 v0, 64, v204
	v_mul_lo_u16_e32 v4, 43, v0
	v_lshrrev_b16_e32 v10, 10, v4
	v_mul_lo_u16_e32 v4, 24, v10
	v_sub_u16_e32 v0, v0, v4
	v_or_b32_e32 v4, s0, v10
	v_lshlrev_b32_sdwa v0, v217, v0 dst_sel:DWORD dst_unused:UNUSED_PAD src0_sel:DWORD src1_sel:BYTE_0
	v_mul_u32_u24_e32 v10, 0x190, v10
	v_add3_u32 v53, s5, v10, v0
	v_bitop3_b16 v10, v204, s42, v214 bitop3:0xc8
	v_mul_lo_u16_e32 v10, 0xab, v10
	v_mad_i64_i32 v[4:5], s[8:9], v4, s40, v[46:47]
	v_lshrrev_b16_e32 v12, 12, v10
	v_lshl_add_u64 v[6:7], v[4:5], 0, v[0:1]
	v_or_b32_e32 v0, 0xffffff80, v204
	v_mul_lo_u16_e32 v10, 24, v12
	v_sub_u16_e32 v0, v0, v10
	v_or_b32_e32 v10, s0, v12
	v_lshlrev_b32_sdwa v0, v217, v0 dst_sel:DWORD dst_unused:UNUSED_PAD src0_sel:DWORD src1_sel:BYTE_0
	v_mul_u32_u24_e32 v12, 0x190, v12
	v_add3_u32 v54, s5, v12, v0
	v_bitop3_b16 v12, v208, s35, v215 bitop3:0xc8
	v_mul_lo_u16_e32 v12, 0xab, v12
	v_mad_i64_i32 v[10:11], s[8:9], v10, s40, v[46:47]
	v_lshrrev_b16_e32 v18, 12, v12
	v_lshl_add_u64 v[10:11], v[10:11], 0, v[0:1]
	v_or_b32_e32 v0, 0xffffffc0, v208
	v_mul_lo_u16_e32 v12, 24, v18
	v_sub_u16_e32 v0, v0, v12
	v_or_b32_e32 v12, s0, v18
	v_mad_i64_i32 v[12:13], s[8:9], v12, s40, v[46:47]
	v_lshlrev_b32_sdwa v0, v217, v0 dst_sel:DWORD dst_unused:UNUSED_PAD src0_sel:DWORD src1_sel:BYTE_0
	v_mul_u32_u24_e32 v18, 0x190, v18
	v_lshl_add_u64 v[14:15], v[12:13], 0, v[0:1]
	v_add3_u32 v55, s5, v18, v0
	v_or_b32_e32 v0, 0x100, v204
	v_mul_u32_u24_sdwa v20, v0, s43 dst_sel:DWORD dst_unused:UNUSED_PAD src0_sel:WORD_0 src1_sel:DWORD
	v_mul_lo_u16_sdwa v18, v20, v218 dst_sel:DWORD dst_unused:UNUSED_PAD src0_sel:WORD_1 src1_sel:DWORD
	v_sub_u16_e32 v0, v0, v18
	v_or_b32_sdwa v18, s0, v20 dst_sel:DWORD dst_unused:UNUSED_PAD src0_sel:DWORD src1_sel:WORD_1
	v_mad_i64_i32 v[18:19], s[8:9], v18, s40, v[46:47]
	v_lshlrev_b32_e32 v0, 4, v0
	v_mul_u32_u24_sdwa v20, v20, s41 dst_sel:DWORD dst_unused:UNUSED_PAD src0_sel:WORD_1 src1_sel:DWORD
	v_lshl_add_u64 v[18:19], v[18:19], 0, v[0:1]
	v_add3_u32 v56, s5, v20, v0
	v_or_b32_e32 v0, 0x140, v204
	v_mul_u32_u24_sdwa v26, v0, s43 dst_sel:DWORD dst_unused:UNUSED_PAD src0_sel:WORD_0 src1_sel:DWORD
	v_mul_lo_u16_sdwa v20, v26, v218 dst_sel:DWORD dst_unused:UNUSED_PAD src0_sel:WORD_1 src1_sel:DWORD
	v_sub_u16_e32 v0, v0, v20
	v_or_b32_sdwa v20, s0, v26 dst_sel:DWORD dst_unused:UNUSED_PAD src0_sel:DWORD src1_sel:WORD_1
	v_mad_i64_i32 v[20:21], s[8:9], v20, s40, v[46:47]
	v_lshlrev_b32_e32 v0, 4, v0
	v_mul_u32_u24_sdwa v26, v26, s41 dst_sel:DWORD dst_unused:UNUSED_PAD src0_sel:WORD_1 src1_sel:DWORD
	v_lshl_add_u64 v[22:23], v[20:21], 0, v[0:1]
	v_add3_u32 v57, s5, v26, v0
	v_or_b32_e32 v0, 0x180, v204
	v_mul_u32_u24_sdwa v28, v0, s43 dst_sel:DWORD dst_unused:UNUSED_PAD src0_sel:WORD_0 src1_sel:DWORD
	v_mul_lo_u16_sdwa v26, v28, v218 dst_sel:DWORD dst_unused:UNUSED_PAD src0_sel:WORD_1 src1_sel:DWORD
	v_sub_u16_e32 v0, v0, v26
	v_or_b32_sdwa v26, s0, v28 dst_sel:DWORD dst_unused:UNUSED_PAD src0_sel:DWORD src1_sel:WORD_1
	v_mad_i64_i32 v[26:27], s[8:9], v26, s40, v[46:47]
	v_lshlrev_b32_e32 v0, 4, v0
	v_mul_u32_u24_sdwa v28, v28, s41 dst_sel:DWORD dst_unused:UNUSED_PAD src0_sel:WORD_1 src1_sel:DWORD
	v_lshl_add_u64 v[26:27], v[26:27], 0, v[0:1]
	v_add3_u32 v58, s5, v28, v0
	v_or_b32_e32 v0, 0x1c0, v204
	v_mul_u32_u24_sdwa v34, v0, s43 dst_sel:DWORD dst_unused:UNUSED_PAD src0_sel:WORD_0 src1_sel:DWORD
	v_mul_lo_u16_sdwa v28, v34, v218 dst_sel:DWORD dst_unused:UNUSED_PAD src0_sel:WORD_1 src1_sel:DWORD
	v_sub_u16_e32 v0, v0, v28
	v_or_b32_sdwa v28, s0, v34 dst_sel:DWORD dst_unused:UNUSED_PAD src0_sel:DWORD src1_sel:WORD_1
	v_mad_i64_i32 v[28:29], s[8:9], v28, s40, v[46:47]
	v_lshlrev_b32_e32 v0, 4, v0
	v_mul_u32_u24_sdwa v34, v34, s41 dst_sel:DWORD dst_unused:UNUSED_PAD src0_sel:WORD_1 src1_sel:DWORD
	v_lshl_add_u64 v[30:31], v[28:29], 0, v[0:1]
	v_add3_u32 v59, s5, v34, v0
	v_or_b32_e32 v0, 0x200, v204
	v_mul_u32_u24_sdwa v36, v0, s43 dst_sel:DWORD dst_unused:UNUSED_PAD src0_sel:WORD_0 src1_sel:DWORD
	v_mul_lo_u16_sdwa v34, v36, v218 dst_sel:DWORD dst_unused:UNUSED_PAD src0_sel:WORD_1 src1_sel:DWORD
	v_sub_u16_e32 v0, v0, v34
	v_or_b32_sdwa v34, s0, v36 dst_sel:DWORD dst_unused:UNUSED_PAD src0_sel:DWORD src1_sel:WORD_1
	v_mad_i64_i32 v[34:35], s[8:9], v34, s40, v[46:47]
	v_lshlrev_b32_e32 v0, 4, v0
	v_mul_u32_u24_sdwa v36, v36, s41 dst_sel:DWORD dst_unused:UNUSED_PAD src0_sel:WORD_1 src1_sel:DWORD
	v_lshl_add_u64 v[34:35], v[34:35], 0, v[0:1]
	v_add3_u32 v60, s5, v36, v0
	v_or_b32_e32 v0, 0x240, v204
	v_mul_u32_u24_sdwa v42, v0, s43 dst_sel:DWORD dst_unused:UNUSED_PAD src0_sel:WORD_0 src1_sel:DWORD
	v_mul_lo_u16_sdwa v36, v42, v218 dst_sel:DWORD dst_unused:UNUSED_PAD src0_sel:WORD_1 src1_sel:DWORD
	v_sub_u16_e32 v0, v0, v36
	v_or_b32_sdwa v36, s0, v42 dst_sel:DWORD dst_unused:UNUSED_PAD src0_sel:DWORD src1_sel:WORD_1
	v_mad_i64_i32 v[36:37], s[8:9], v36, s40, v[46:47]
	v_lshlrev_b32_e32 v0, 4, v0
	v_mul_u32_u24_sdwa v42, v42, s41 dst_sel:DWORD dst_unused:UNUSED_PAD src0_sel:WORD_1 src1_sel:DWORD
	v_lshl_add_u64 v[38:39], v[36:37], 0, v[0:1]
	v_add3_u32 v61, s5, v42, v0
	v_or_b32_e32 v0, 0x280, v204
	v_mul_u32_u24_sdwa v48, v0, s43 dst_sel:DWORD dst_unused:UNUSED_PAD src0_sel:WORD_0 src1_sel:DWORD
	v_mul_lo_u16_sdwa v42, v48, v218 dst_sel:DWORD dst_unused:UNUSED_PAD src0_sel:WORD_1 src1_sel:DWORD
	v_sub_u16_e32 v0, v0, v42
	v_or_b32_sdwa v42, s0, v48 dst_sel:DWORD dst_unused:UNUSED_PAD src0_sel:DWORD src1_sel:WORD_1
	v_mad_i64_i32 v[42:43], s[8:9], v42, s40, v[46:47]
	v_lshlrev_b32_e32 v0, 4, v0
	v_mul_u32_u24_sdwa v48, v48, s41 dst_sel:DWORD dst_unused:UNUSED_PAD src0_sel:WORD_1 src1_sel:DWORD
	v_lshl_add_u64 v[42:43], v[42:43], 0, v[0:1]
	v_add3_u32 v62, s5, v48, v0
	v_or_b32_e32 v0, 0x2c0, v204
	v_readlane_b32 s16, v246, 0
	v_mul_u32_u24_sdwa v63, v0, s43 dst_sel:DWORD dst_unused:UNUSED_PAD src0_sel:WORD_0 src1_sel:DWORD
	v_readlane_b32 s20, v246, 4
	v_readlane_b32 s21, v246, 5
	v_mul_lo_u16_sdwa v48, v63, v218 dst_sel:DWORD dst_unused:UNUSED_PAD src0_sel:WORD_1 src1_sel:DWORD
	s_mov_b64 s[2:3], s[20:21]
	v_sub_u16_e32 v0, v0, v48
	v_or_b32_sdwa v48, s0, v63 dst_sel:DWORD dst_unused:UNUSED_PAD src0_sel:DWORD src1_sel:WORD_1
	global_load_dwordx4 v[2:5], v[2:3], off nt
	s_nop 0
	global_load_dwordx4 v[6:9], v[6:7], off nt
	s_nop 0
	global_load_dwordx4 v[10:13], v[10:11], off nt
	s_nop 0
	global_load_dwordx4 v[14:17], v[14:15], off nt
	s_nop 0
	global_load_dwordx4 v[18:21], v[18:19], off nt
	s_nop 0
	global_load_dwordx4 v[22:25], v[22:23], off nt
	s_nop 0
	global_load_dwordx4 v[26:29], v[26:27], off nt
	s_nop 0
	global_load_dwordx4 v[30:33], v[30:31], off nt
	s_nop 0
	global_load_dwordx4 v[34:37], v[34:35], off nt
	s_nop 0
	global_load_dwordx4 v[38:41], v[38:39], off nt
	v_mad_i64_i32 v[46:47], s[8:9], v48, s40, v[46:47]
	v_lshlrev_b32_e32 v0, 4, v0
	v_lshl_add_u64 v[46:47], v[46:47], 0, v[0:1]
	global_load_dwordx4 v[42:45], v[42:43], off nt
	v_bfe_u32 v231, v208, 5, 1
	global_load_dwordx4 v[46:49], v[46:47], off nt
	s_waitcnt vmcnt(11)
	ds_write_b128 v52, v[2:5]
	s_waitcnt vmcnt(10)
	ds_write_b128 v53, v[6:9]
	s_waitcnt vmcnt(9)
	ds_write_b128 v54, v[10:13]
	s_waitcnt vmcnt(8)
	ds_write_b128 v55, v[14:17]
	s_waitcnt vmcnt(7)
	ds_write_b128 v56, v[18:21]
	s_waitcnt vmcnt(6)
	ds_write_b128 v57, v[22:25]
	s_waitcnt vmcnt(5)
	ds_write_b128 v58, v[26:29]
	s_waitcnt vmcnt(4)
	ds_write_b128 v59, v[30:33]
	s_waitcnt vmcnt(3)
	ds_write_b128 v60, v[34:37]
	s_waitcnt vmcnt(2)
	ds_write_b128 v61, v[38:41]
	s_waitcnt vmcnt(1)
	ds_write_b128 v62, v[42:45]
	v_mul_u32_u24_sdwa v2, v63, s41 dst_sel:DWORD dst_unused:UNUSED_PAD src0_sel:WORD_1 src1_sel:DWORD
	v_add3_u32 v0, s5, v2, v0
	v_lshlrev_b32_e32 v206, 4, v231
	v_lshlrev_b64 v[2:3], 7, v[50:51]
	v_lshl_add_u64 v[50:51], s[62:63], 0, v[2:3]
	v_readlane_b32 s22, v246, 6
	s_waitcnt vmcnt(0)
	ds_write_b128 v0, v[46:49]
	v_mul_u32_u24_e32 v0, 0x190, v205
	v_add3_u32 v0, s5, v0, v206
	ds_read_b128 v[42:45], v0
	ds_read_b128 v[18:21], v0 offset:32
	ds_read_b128 v[38:41], v0 offset:64
	ds_read_b128 v[26:29], v0 offset:96
	ds_read_b128 v[34:37], v0 offset:128
	ds_read_b128 v[22:25], v0 offset:160
	s_waitcnt lgkmcnt(5)
	v_and_b32_e32 v3, 0xffff0000, v42
	v_lshlrev_b32_e32 v2, 16, v42
	v_mul_f32_e32 v112, v3, v3
	v_lshlrev_b32_e32 v4, 16, v43
	v_fmac_f32_e32 v112, v2, v2
	v_and_b32_e32 v5, 0xffff0000, v43
	v_fmac_f32_e32 v112, v4, v4
	v_lshlrev_b32_e32 v6, 16, v44
	v_fmac_f32_e32 v112, v5, v5
	v_and_b32_e32 v7, 0xffff0000, v44
	v_fmac_f32_e32 v112, v6, v6
	v_lshlrev_b32_e32 v8, 16, v45
	v_fmac_f32_e32 v112, v7, v7
	v_and_b32_e32 v9, 0xffff0000, v45
	v_fmac_f32_e32 v112, v8, v8
	v_fmac_f32_e32 v112, v9, v9
	s_waitcnt lgkmcnt(4)
	v_lshlrev_b32_e32 v2, 16, v18
	v_and_b32_e32 v3, 0xffff0000, v18
	v_fmac_f32_e32 v112, v2, v2
	v_lshlrev_b32_e32 v4, 16, v19
	v_fmac_f32_e32 v112, v3, v3
	v_and_b32_e32 v5, 0xffff0000, v19
	v_fmac_f32_e32 v112, v4, v4
	v_lshlrev_b32_e32 v6, 16, v20
	v_fmac_f32_e32 v112, v5, v5
	v_and_b32_e32 v7, 0xffff0000, v20
	v_fmac_f32_e32 v112, v6, v6
	v_lshlrev_b32_e32 v8, 16, v21
	v_fmac_f32_e32 v112, v7, v7
	v_and_b32_e32 v9, 0xffff0000, v21
	v_fmac_f32_e32 v112, v8, v8
	v_fmac_f32_e32 v112, v9, v9
	s_waitcnt lgkmcnt(3)
	v_lshlrev_b32_e32 v2, 16, v38
	v_and_b32_e32 v3, 0xffff0000, v38
	v_fmac_f32_e32 v112, v2, v2
	v_lshlrev_b32_e32 v4, 16, v39
	v_fmac_f32_e32 v112, v3, v3
	v_and_b32_e32 v5, 0xffff0000, v39
	v_fmac_f32_e32 v112, v4, v4
	v_lshlrev_b32_e32 v6, 16, v40
	v_fmac_f32_e32 v112, v5, v5
	v_and_b32_e32 v7, 0xffff0000, v40
	v_fmac_f32_e32 v112, v6, v6
	v_lshlrev_b32_e32 v8, 16, v41
	v_fmac_f32_e32 v112, v7, v7
	v_and_b32_e32 v9, 0xffff0000, v41
	v_fmac_f32_e32 v112, v8, v8
	v_fmac_f32_e32 v112, v9, v9
	s_waitcnt lgkmcnt(2)
	v_lshlrev_b32_e32 v2, 16, v26
	v_and_b32_e32 v3, 0xffff0000, v26
	v_fmac_f32_e32 v112, v2, v2
	v_lshlrev_b32_e32 v4, 16, v27
	v_fmac_f32_e32 v112, v3, v3
	v_and_b32_e32 v5, 0xffff0000, v27
	v_fmac_f32_e32 v112, v4, v4
	v_lshlrev_b32_e32 v6, 16, v28
	v_fmac_f32_e32 v112, v5, v5
	v_and_b32_e32 v7, 0xffff0000, v28
	v_fmac_f32_e32 v112, v6, v6
	v_lshlrev_b32_e32 v8, 16, v29
	v_fmac_f32_e32 v112, v7, v7
	v_and_b32_e32 v9, 0xffff0000, v29
	v_fmac_f32_e32 v112, v8, v8
	v_fmac_f32_e32 v112, v9, v9
	s_waitcnt lgkmcnt(1)
	v_lshlrev_b32_e32 v2, 16, v34
	v_and_b32_e32 v3, 0xffff0000, v34
	v_fmac_f32_e32 v112, v2, v2
	v_lshlrev_b32_e32 v4, 16, v35
	v_fmac_f32_e32 v112, v3, v3
	v_and_b32_e32 v5, 0xffff0000, v35
	v_fmac_f32_e32 v112, v4, v4
	v_lshlrev_b32_e32 v6, 16, v36
	v_fmac_f32_e32 v112, v5, v5
	v_and_b32_e32 v7, 0xffff0000, v36
	v_fmac_f32_e32 v112, v6, v6
	v_lshlrev_b32_e32 v8, 16, v37
	v_fmac_f32_e32 v112, v7, v7
	v_and_b32_e32 v9, 0xffff0000, v37
	v_fmac_f32_e32 v112, v8, v8
	v_fmac_f32_e32 v112, v9, v9
	s_waitcnt lgkmcnt(0)
	v_lshlrev_b32_e32 v2, 16, v22
	v_and_b32_e32 v3, 0xffff0000, v22
	v_fmac_f32_e32 v112, v2, v2
	v_lshlrev_b32_e32 v4, 16, v23
	v_fmac_f32_e32 v112, v3, v3
	v_and_b32_e32 v5, 0xffff0000, v23
	v_fmac_f32_e32 v112, v4, v4
	ds_read_b128 v[30:33], v0 offset:192
	ds_read_b128 v[14:17], v0 offset:224
	v_lshlrev_b32_e32 v6, 16, v24
	v_fmac_f32_e32 v112, v5, v5
	v_and_b32_e32 v7, 0xffff0000, v24
	v_fmac_f32_e32 v112, v6, v6
	v_lshlrev_b32_e32 v8, 16, v25
	v_fmac_f32_e32 v112, v7, v7
	v_and_b32_e32 v9, 0xffff0000, v25
	v_fmac_f32_e32 v112, v8, v8
	v_fmac_f32_e32 v112, v9, v9
	s_waitcnt lgkmcnt(1)
	v_lshlrev_b32_e32 v2, 16, v30
	v_and_b32_e32 v3, 0xffff0000, v30
	v_fmac_f32_e32 v112, v2, v2
	v_lshlrev_b32_e32 v4, 16, v31
	v_fmac_f32_e32 v112, v3, v3
	v_and_b32_e32 v5, 0xffff0000, v31
	v_fmac_f32_e32 v112, v4, v4
	v_lshlrev_b32_e32 v6, 16, v32
	v_fmac_f32_e32 v112, v5, v5
	v_and_b32_e32 v7, 0xffff0000, v32
	v_fmac_f32_e32 v112, v6, v6
	v_lshlrev_b32_e32 v8, 16, v33
	v_fmac_f32_e32 v112, v7, v7
	v_and_b32_e32 v9, 0xffff0000, v33
	v_fmac_f32_e32 v112, v8, v8
	v_fmac_f32_e32 v112, v9, v9
	s_waitcnt lgkmcnt(0)
	v_lshlrev_b32_e32 v2, 16, v14
	v_and_b32_e32 v3, 0xffff0000, v14
	v_fmac_f32_e32 v112, v2, v2
	v_lshlrev_b32_e32 v4, 16, v15
	v_fmac_f32_e32 v112, v3, v3
	v_and_b32_e32 v5, 0xffff0000, v15
	v_fmac_f32_e32 v112, v4, v4
	v_lshlrev_b32_e32 v10, 16, v16
	v_fmac_f32_e32 v112, v5, v5
	v_and_b32_e32 v11, 0xffff0000, v16
	v_fmac_f32_e32 v112, v10, v10
	ds_read_b128 v[6:9], v0 offset:256
	ds_read_b128 v[2:5], v0 offset:288
	v_fmac_f32_e32 v112, v11, v11
	ds_read_b128 v[46:49], v0 offset:320
	ds_read_b128 v[10:13], v0 offset:352
	v_readlane_b32 s23, v246, 7
	v_and_b32_e32 v0, 32, v208
	v_lshl_add_u64 v[52:53], v[50:51], 0, s[44:45]
	v_readlane_b32 s20, v245, 24
	v_lshl_add_u64 v[62:63], s[2:3], 0, v[0:1]
	v_lshl_add_u64 v[54:55], v[50:51], 0, v[0:1]
	v_lshl_add_u64 v[50:51], v[52:53], 0, v[0:1]
	v_or_b32_e32 v0, 64, v0
	v_readlane_b32 s22, v245, 26
	v_readlane_b32 s23, v245, 27
	v_lshl_add_u64 v[58:59], v[52:53], 0, v[0:1]
	v_lshlrev_b32_e32 v207, 4, v208
	v_readlane_b32 s21, v245, 25
	s_mov_b32 s22, s14
	s_mov_b32 s23, s15
	v_lshlrev_b32_e32 v113, 16, v17
	v_and_b32_e32 v124, 0xffff0000, v17
	s_waitcnt lgkmcnt(3)
	v_lshlrev_b32_e32 v125, 16, v6
	v_and_b32_e32 v126, 0xffff0000, v6
	v_lshlrev_b32_e32 v128, 16, v7
	v_and_b32_e32 v129, 0xffff0000, v7
	v_lshlrev_b32_e32 v130, 16, v8
	v_and_b32_e32 v131, 0xffff0000, v8
	v_lshlrev_b32_e32 v200, 16, v9
	v_and_b32_e32 v201, 0xffff0000, v9
	s_waitcnt lgkmcnt(2)
	v_lshlrev_b32_e32 v202, 16, v2
	v_and_b32_e32 v203, 0xffff0000, v2
	v_lshlrev_b32_e32 v209, 16, v3
	v_and_b32_e32 v227, 0xffff0000, v3
	v_lshlrev_b32_e32 v228, 16, v4
	v_and_b32_e32 v229, 0xffff0000, v4
	v_lshlrev_b32_e32 v232, 16, v5
	v_and_b32_e32 v233, 0xffff0000, v5
	s_waitcnt lgkmcnt(1)
	v_lshlrev_b32_e32 v234, 16, v46
	v_and_b32_e32 v235, 0xffff0000, v46
	v_lshlrev_b32_e32 v236, 16, v47
	v_and_b32_e32 v237, 0xffff0000, v47
	v_lshlrev_b32_e32 v238, 16, v48
	v_and_b32_e32 v239, 0xffff0000, v48
	v_lshlrev_b32_e32 v240, 16, v49
	v_and_b32_e32 v241, 0xffff0000, v49
	s_waitcnt lgkmcnt(0)
	v_and_b32_e32 v114, 0xffff0000, v10
	v_lshlrev_b32_e32 v115, 16, v10
	v_and_b32_e32 v116, 0xffff0000, v11
	v_lshlrev_b32_e32 v117, 16, v11
	v_and_b32_e32 v118, 0xffff0000, v12
	v_lshlrev_b32_e32 v119, 16, v12
	v_and_b32_e32 v110, 0xffff0000, v13
	v_lshlrev_b32_e32 v111, 16, v13
	flat_load_dwordx4 v[132:135], v[62:63]
	flat_load_dwordx4 v[196:199], v[62:63] offset:16
	flat_load_dwordx4 v[136:139], v[62:63] offset:64
	flat_load_dwordx4 v[192:195], v[62:63] offset:80
	flat_load_dwordx4 v[140:143], v[62:63] offset:128
	flat_load_dwordx4 v[188:191], v[62:63] offset:144
	flat_load_dwordx4 v[144:147], v[62:63] offset:192
	flat_load_dwordx4 v[184:187], v[62:63] offset:208
	flat_load_dwordx4 v[148:151], v[62:63] offset:256
	flat_load_dwordx4 v[180:183], v[62:63] offset:272
	flat_load_dwordx4 v[152:155], v[62:63] offset:320
	flat_load_dwordx4 v[176:179], v[62:63] offset:336
	flat_load_dwordx4 v[156:159], v[62:63] offset:384
	flat_load_dwordx4 v[172:175], v[62:63] offset:400
	flat_load_dwordx4 v[160:163], v[62:63] offset:448
	flat_load_dwordx4 v[168:171], v[62:63] offset:464
	global_load_dwordx4 v[82:85], v[54:55], off offset:16
	global_load_dwordx4 v[98:101], v[54:55], off
	global_load_dwordx4 v[86:89], v[50:51], off offset:16
	global_load_dwordx4 v[102:105], v[50:51], off
	flat_load_dwordx4 v[106:109], v[62:63] offset:512
	flat_load_dwordx4 v[90:93], v[62:63] offset:528
	flat_load_dwordx4 v[164:167], v[62:63] offset:640
	flat_load_dwordx4 v[94:97], v[62:63] offset:656
	s_nop 0
	global_load_dwordx4 v[50:53], v[54:55], off offset:80
	global_load_dwordx4 v[66:69], v[54:55], off offset:64
	s_nop 0
	global_load_dwordx4 v[54:57], v[58:59], off offset:16
	global_load_dwordx4 v[70:73], v[58:59], off
	flat_load_dwordx4 v[74:77], v[62:63] offset:576
	s_nop 0
	flat_load_dwordx4 v[58:61], v[62:63] offset:592
	flat_load_dwordx4 v[78:81], v[62:63] offset:704
	s_nop 0
	flat_load_dwordx4 v[62:65], v[62:63] offset:720
	s_waitcnt lgkmcnt(0)
	s_barrier
	buffer_load_dwordx4 v[120:123], v207, s[20:23], 0 offen
	v_fmac_f32_e32 v112, v113, v113
	v_fmac_f32_e32 v112, v124, v124
	v_fmac_f32_e32 v112, v125, v125
	v_fmac_f32_e32 v112, v126, v126
	buffer_load_dwordx4 v[124:127], v207, s[20:23], s47 offen
	v_fmac_f32_e32 v112, v128, v128
	v_fmac_f32_e32 v112, v129, v129
	v_fmac_f32_e32 v112, v130, v130
	v_fmac_f32_e32 v112, v131, v131
	buffer_load_dwordx4 v[128:131], v207, s[20:23], s48 offen
	v_fmac_f32_e32 v112, v200, v200
	v_fmac_f32_e32 v112, v201, v201
	v_fmac_f32_e32 v112, v202, v202
	v_fmac_f32_e32 v112, v203, v203
	v_fmac_f32_e32 v112, v209, v209
	v_fmac_f32_e32 v112, v227, v227
	v_fmac_f32_e32 v112, v228, v228
	v_fmac_f32_e32 v112, v229, v229
	v_fmac_f32_e32 v112, v232, v232
	v_fmac_f32_e32 v112, v233, v233
	v_fmac_f32_e32 v112, v234, v234
	v_fmac_f32_e32 v112, v235, v235
	v_fmac_f32_e32 v112, v236, v236
	v_fmac_f32_e32 v112, v237, v237
	v_fmac_f32_e32 v112, v238, v238
	v_fmac_f32_e32 v112, v239, v239
	v_fmac_f32_e32 v112, v240, v240
	v_fmac_f32_e32 v112, v241, v241
	v_pk_mul_f32 v[114:115], v[114:115], v[114:115]
	v_mul_hi_i32 v200, v208, s46
	v_add_f32_e32 v0, v115, v112
	v_readlane_b32 s24, v246, 8
	v_readlane_b32 s25, v246, 9
	v_readlane_b32 s26, v246, 10
	v_readlane_b32 s27, v246, 11
	v_add_f32_e32 v0, v114, v0
	v_pk_mul_f32 v[112:113], v[116:117], v[116:117]
	v_lshrrev_b32_e32 v201, 31, v200
	v_lshrrev_b32_e32 v200, 2, v200
	v_readlane_b32 s24, v245, 20
	v_add_f32_e32 v0, v113, v0
	v_add_u32_e32 v200, v200, v201
	v_and_b32_e32 v202, 0x70, v207
	v_lshlrev_b32_e32 v114, 11, v208
	v_readlane_b32 s26, v245, 22
	v_readlane_b32 s27, v245, 23
	v_add_f32_e32 v0, v112, v0
	v_pk_mul_f32 v[112:113], v[118:119], v[118:119]
	v_add_lshl_u32 v227, v200, v208, 4
	v_and_or_b32 v209, v114, s49, v202
	v_readlane_b32 s25, v245, 21
	s_mov_b32 s26, s14
	s_mov_b32 s27, s15
	v_add_f32_e32 v0, v113, v0
	v_add_u32_e32 v200, 0, v227
	v_add_f32_e32 v0, v112, v0
	buffer_load_dwordx4 v[232:235], v209, s[24:27], 0 offen
	buffer_load_dwordx4 v[236:239], v209, s[24:27], s50 offen
	buffer_load_dwordx4 v[112:115], v207, s[20:23], s55 offen
	buffer_load_dwordx4 v[116:119], v207, s[20:23], s56 offen
	v_pk_mul_f32 v[110:111], v[110:111], v[110:111]
	s_cmp_gt_i32 s7, 3
	v_add_f32_e32 v0, v111, v0
	v_add_f32_e32 v0, v110, v0
	ds_bpermute_b32 v110, v212, v0
	v_readlane_b32 s17, v246, 1
	v_readlane_b32 s18, v246, 2
	v_readlane_b32 s19, v246, 3
	v_readlane_b32 s28, v246, 12
	s_waitcnt lgkmcnt(0)
	v_add_f32_e32 v0, v0, v110
	v_mul_f32_e32 v110, v230, v230
	v_mul_f32_e32 v0, v110, v0
	v_fmamk_f32 v0, v0, 0x3baaaaab, v216
	v_mul_f32_e32 v110, 0x4b800000, v0
	v_cmp_gt_f32_e32 vcc, s54, v0
	v_readlane_b32 s29, v246, 13
	v_readlane_b32 s30, v246, 14
	v_cndmask_b32_e32 v0, v0, v110, vcc
	v_lshrrev_b32_e32 v110, 3, v208
	v_readlane_b32 s31, v246, 15
	s_waitcnt vmcnt(0)
	ds_write_b128 v200, v[120:123]
	v_add_u32_e32 v200, 0x200, v208
	v_mul_hi_i32 v201, v200, s46
	v_lshrrev_b32_e32 v203, 31, v201
	v_lshrrev_b32_e32 v201, 2, v201
	v_add_u32_e32 v201, v201, v203
	v_add_lshl_u32 v228, v201, v200, 4
	v_add_u32_e32 v201, 0x400, v208
	v_add_u32_e32 v203, 0, v228
	ds_write_b128 v203, v[124:127]
	v_mul_hi_i32 v124, v201, s46
	v_lshrrev_b32_e32 v125, 31, v124
	v_lshrrev_b32_e32 v124, 2, v124
	v_add_u32_e32 v203, v124, v125
	v_add_lshl_u32 v229, v203, v201, 4
	v_add_u32_e32 v201, 0, v229
	buffer_load_dwordx4 v[120:123], v207, s[20:23], s57 offen
	buffer_load_dwordx4 v[124:127], v209, s[24:27], s58 offen
	ds_write_b128 v201, v[128:131]
	buffer_load_dwordx4 v[128:131], v209, s[24:27], s59 offen
	v_lshrrev_b32_e32 v111, 3, v200
	v_mad_u64_u32 v[200:201], s[2:3], v110, s51, v[202:203]
	v_add_u32_e32 v110, 0, v200
	v_mad_u64_u32 v[202:203], s[2:3], v111, s51, v[202:203]
	s_cselect_b64 s[2:3], -1, 0
	s_cmp_lt_i32 s7, 4
	ds_write_b128 v110, v[232:235] offset:25600
	v_add_u32_e32 v110, 0, v202
	ds_write_b128 v110, v[236:239] offset:25600
	s_waitcnt lgkmcnt(0)
	s_barrier
	s_cbranch_scc1 .LBB0_708
	s_nop 0
